# P2a->P2b barrier as one-way two-level signal: per-XCD count-in, last of XCD writes back L2 and bumps chip word; only RWKV blocks wait
# speedup vs baseline: 1.0116x; 1.0116x over previous
.LBB0_290:
	s_mov_b64 s[4:5], s[76:77]
	s_mov_b32 s1, s97
	s_mov_b32 s2, -1
	s_getreg_b32 s0, hwreg(HW_REG_XCC_ID, 0, 4)
	s_waitcnt vmcnt(0)
	s_nop 0
	v_mbcnt_lo_u32_b32 v0, s2, 0
	v_mbcnt_hi_u32_b32 v0, s2, v0
	v_lshl_or_b32 v0, s1, 6, v0
	v_cmp_eq_u32_e32 vcc, 0, v0
	s_barrier
	s_and_saveexec_b64 s[2:3], vcc
	s_cbranch_execz .LBB0_342
	s_load_dwordx2 s[6:7], s[4:5], 0xe0
	v_mov_b32_e32 v0, s78
	ds_read_b32 v2, v0
	v_mov_b32_e32 v0, s79
	ds_read_b32 v4, v0
	s_and_b32 s0, s0, 15
	s_lshl_b32 s1, s90, 12
	s_lshl_b32 s0, s0, 4
	v_mov_b32_e32 v1, 0
	v_mov_b32_e32 v0, 1
	s_waitcnt lgkmcnt(0)
	s_add_u32 s8, s6, s1
	s_addc_u32 s9, s7, 0
	s_add_u32 s8, s8, 0xc000
	s_addc_u32 s9, s9, 0
	s_add_u32 s10, s8, s0
	s_addc_u32 s11, s9, 0
	global_atomic_add v5, v1, v0, s[10:11] offset:3712 sc0
	s_waitcnt vmcnt(0)
	v_add_u32_e32 v5, 1, v5
	v_cmp_eq_u32_e32 vcc, v5, v2
	s_cbranch_vccz .Lsig_notlast
	buffer_wbl2 sc1
	s_waitcnt vmcnt(0)
	global_atomic_add v1, v0, s[8:9] offset:4032
.Lsig_notlast:
	s_cmpk_lt_u32 s96, 0xb0
	s_cbranch_scc1 .Lsig_skip
	s_cmpk_gt_u32 s96, 0xef
	s_cbranch_scc1 .Lsig_skip
	s_mov_b32 s0, 0
.Lsig_spin:
	global_load_dword v5, v1, s[8:9] offset:4032 sc1
	s_add_i32 s0, s0, 1
	s_waitcnt vmcnt(0)
	v_cmp_lt_u32_e32 vcc, v5, v4
	s_cbranch_vccz .Lsig_got
	s_sleep 1
	s_cmp_lt_u32 s0, 0x20000
	s_cbranch_scc1 .Lsig_spin
